# ph15 main loop: one dummy load per iteration keeps the unit's row-norm (ss) lines hot in L2 for the epilogue
# baseline (speedup 1.0000x reference)
.LBB0_1401:
	s_lshl_b32 s18, s42, 14
	v_lshl_add_u32 v253, v179, 5, s18
	s_add_i32 s72, s72, 1
	s_mul_i32 s18, s72, s15
	s_mul_hi_u32 s19, s72, s64
	s_add_i32 s19, s19, s18
	s_mul_i32 s18, s72, s64
	s_add_u32 s18, s18, s16
	s_addc_u32 s19, s19, s57
	v_cmp_gt_i64_e32 vcc, s[18:19], v[192:193]
	v_cmp_lt_i64_e64 s[40:41], s[18:19], v[190:191]
	s_cbranch_vccnz .LBB0_1403
	s_ashr_i32 s19, s18, 31
	s_lshr_b32 s19, s19, 29
	s_add_i32 s19, s18, s19
	s_ashr_i32 s44, s19, 3
	s_and_b32 s19, s19, -8
	s_sub_i32 s18, s18, s19
	s_cmp_lt_i32 s18, 0
	s_movk_i32 s19, 0xa1
	s_cselect_b32 s19, s19, 0xa0
	s_mul_i32 s18, s19, s18
	s_add_i32 s18, s18, s44
	s_ashr_i32 s19, s18, 31
	s_lshr_b32 s19, s19, 26
	s_add_i32 s19, s18, s19
	s_ashr_i32 s44, s19, 6
	s_lshl_b32 s45, s44, 2
	s_sub_i32 s44, 0x50, s45
	s_min_i32 s46, s44, 4
	s_abs_i32 s44, s46
	v_cvt_f32_u32_e32 v0, s44
	s_sub_i32 s48, 0, s44
	s_andn2_b32 s19, s19, 63
	s_sub_i32 s18, s18, s19
	v_rcp_iflag_f32_e32 v0, v0
	s_abs_i32 s19, s18
	s_xor_b32 s47, s18, s46
	s_ashr_i32 s47, s47, 31
	v_mul_f32_e32 v0, 0x4f7ffffe, v0
	v_cvt_u32_f32_e32 v0, v0
	s_nop 0
	v_readfirstlane_b32 s49, v0
	s_mul_i32 s48, s48, s49
	s_mul_hi_u32 s48, s49, s48
	s_add_i32 s49, s49, s48
	s_mul_hi_u32 s48, s19, s49
	s_mul_i32 s49, s48, s44
	s_sub_i32 s19, s19, s49
	s_add_i32 s50, s48, 1
	s_sub_i32 s49, s19, s44
	s_cmp_ge_u32 s19, s44
	s_cselect_b32 s48, s50, s48
	s_cselect_b32 s19, s49, s19
	s_add_i32 s49, s48, 1
	s_cmp_ge_u32 s19, s44
	s_cselect_b32 s19, s49, s48
	s_xor_b32 s19, s19, s47
	s_sub_i32 s44, s19, s47
	s_mul_i32 s19, s44, s46
	s_sub_i32 s18, s18, s19
	s_add_i32 s46, s18, s45

.LBB0_1405:
	s_add_i32 s83, s18, 2
	s_cmp_eq_u32 s22, s18
	s_cselect_b32 s18, s47, s79
	s_cselect_b32 s19, s45, s80
	s_cselect_b32 s54, s78, s81
	s_cselect_b32 s55, s73, s82
	s_add_u32 s26, s18, 0x80
	s_addc_u32 s27, s19, 0
	s_add_i32 s86, 0, 0x10000
	v_add_u32_e32 v0, s86, v215
	s_add_i32 s87, 0, 0x14000
	ds_read_b128 v[130:133], v0
	ds_read_b128 v[134:137], v0 offset:1024
	ds_read_b128 v[138:141], v0 offset:2048
	ds_read_b128 v[142:145], v0 offset:3072
	v_add_u32_e32 v0, s87, v215
	ds_read_b128 v[146:149], v0
	ds_read_b128 v[150:153], v0 offset:1024
	ds_read_b128 v[154:157], v0 offset:2048
	ds_read_b128 v[158:161], v0 offset:3072
	s_add_u32 s84, s79, 0x3ff80
	s_addc_u32 s85, s80, 0
	ds_read_b128 v[162:165], v218
	ds_read_b128 v[166:169], v218 offset:1024
	ds_read_b128 v[198:201], v218 offset:2048
	ds_read_b128 v[202:205], v218 offset:3072
	ds_read_b128 v[206:209], v218 offset:4096
	ds_read_b128 v[210:213], v218 offset:5120
	ds_read_b128 v[220:223], v218 offset:6144
	ds_read_b128 v[224:227], v218 offset:7168
	s_add_i32 m0, s60, 0xc000
	v_lshl_add_u64 v[216:217], s[84:85], 0, v[196:197]
	global_load_dword v252, v253, s[30:31]
	global_load_lds_dwordx4 v[216:217], off
	v_lshl_add_u64 v[216:217], s[84:85], 0, v[172:173]
	s_add_i32 m0, s60, 0xe000
	s_nop 0
	global_load_lds_dwordx4 v[216:217], off
	s_waitcnt vmcnt(8)
	s_waitcnt lgkmcnt(0)
	s_barrier
	s_setprio 1
	s_waitcnt lgkmcnt(0)
	v_mfma_f32_16x16x32_bf16 v[122:125], v[130:133], v[162:165], v[122:125]
	v_mfma_f32_16x16x32_bf16 v[126:129], v[138:141], v[162:165], v[126:129]
	v_mfma_f32_16x16x32_bf16 v[106:109], v[130:133], v[198:201], v[106:109]
	v_mfma_f32_16x16x32_bf16 v[110:113], v[138:141], v[198:201], v[110:113]
	v_mfma_f32_16x16x32_bf16 v[90:93], v[130:133], v[206:209], v[90:93]
	v_mfma_f32_16x16x32_bf16 v[94:97], v[138:141], v[206:209], v[94:97]
	v_mfma_f32_16x16x32_bf16 v[74:77], v[130:133], v[220:223], v[74:77]
	v_mfma_f32_16x16x32_bf16 v[78:81], v[138:141], v[220:223], v[78:81]
	v_mfma_f32_16x16x32_bf16 v[122:125], v[134:137], v[166:169], v[122:125]
	v_mfma_f32_16x16x32_bf16 v[126:129], v[142:145], v[166:169], v[126:129]
	v_mfma_f32_16x16x32_bf16 v[106:109], v[134:137], v[202:205], v[106:109]
	v_mfma_f32_16x16x32_bf16 v[110:113], v[142:145], v[202:205], v[110:113]
	v_mfma_f32_16x16x32_bf16 v[90:93], v[134:137], v[210:213], v[90:93]
	v_mfma_f32_16x16x32_bf16 v[94:97], v[142:145], v[210:213], v[94:97]
	v_mfma_f32_16x16x32_bf16 v[74:77], v[134:137], v[224:227], v[74:77]
	v_mfma_f32_16x16x32_bf16 v[78:81], v[142:145], v[224:227], v[78:81]
	v_mfma_f32_16x16x32_bf16 v[114:117], v[146:149], v[162:165], v[114:117]
	v_mfma_f32_16x16x32_bf16 v[118:121], v[154:157], v[162:165], v[118:121]
	v_mfma_f32_16x16x32_bf16 v[98:101], v[146:149], v[198:201], v[98:101]
	v_mfma_f32_16x16x32_bf16 v[102:105], v[154:157], v[198:201], v[102:105]
	v_mfma_f32_16x16x32_bf16 v[82:85], v[146:149], v[206:209], v[82:85]
	v_mfma_f32_16x16x32_bf16 v[86:89], v[154:157], v[206:209], v[86:89]
	v_mfma_f32_16x16x32_bf16 v[66:69], v[146:149], v[220:223], v[66:69]
	v_mfma_f32_16x16x32_bf16 v[70:73], v[154:157], v[220:223], v[70:73]
	v_mfma_f32_16x16x32_bf16 v[114:117], v[150:153], v[166:169], v[114:117]
	v_mfma_f32_16x16x32_bf16 v[118:121], v[158:161], v[166:169], v[118:121]
	v_mfma_f32_16x16x32_bf16 v[98:101], v[150:153], v[202:205], v[98:101]
	v_mfma_f32_16x16x32_bf16 v[102:105], v[158:161], v[202:205], v[102:105]
	v_mfma_f32_16x16x32_bf16 v[82:85], v[150:153], v[210:213], v[82:85]
	v_mfma_f32_16x16x32_bf16 v[86:89], v[158:161], v[210:213], v[86:89]
	v_mfma_f32_16x16x32_bf16 v[66:69], v[150:153], v[224:227], v[66:69]
	v_mfma_f32_16x16x32_bf16 v[70:73], v[158:161], v[224:227], v[70:73]
	s_setprio 0
	s_barrier
	s_mov_b64 s[84:85], s[54:55]
	s_add_i32 s86, s86, s56
	ds_read_b128 v[162:165], v218 offset:16384
	ds_read_b128 v[166:169], v218 offset:17408
	ds_read_b128 v[198:201], v218 offset:18432
	ds_read_b128 v[202:205], v218 offset:19456
	ds_read_b128 v[206:209], v218 offset:20480
	ds_read_b128 v[210:213], v218 offset:21504
	ds_read_b128 v[220:223], v218 offset:22528
	ds_read_b128 v[224:227], v218 offset:23552
	s_mov_b32 m0, s86
	v_lshl_add_u64 v[216:217], s[84:85], 0, v[194:195]
	global_load_lds_dwordx4 v[216:217], off
	s_add_i32 m0, s86, 0x2000
	v_lshl_add_u64 v[216:217], s[84:85], 0, v[170:171]
	s_add_u32 s84, s54, 0x40000
	s_addc_u32 s85, s55, 0
	s_add_i32 s86, s87, s56
	global_load_lds_dwordx4 v[216:217], off
	s_mov_b32 m0, s86
	v_lshl_add_u64 v[216:217], s[84:85], 0, v[194:195]
	global_load_lds_dwordx4 v[216:217], off
	v_lshl_add_u64 v[216:217], s[84:85], 0, v[170:171]
	s_add_i32 m0, s86, 0x2000
	s_mov_b64 s[84:85], s[18:19]
	global_load_lds_dwordx4 v[216:217], off
	s_mov_b32 m0, s60
	v_lshl_add_u64 v[216:217], s[84:85], 0, v[196:197]
	global_load_lds_dwordx4 v[216:217], off
	v_lshl_add_u64 v[216:217], s[84:85], 0, v[172:173]
	s_mov_b32 m0, s61
	s_nop 0
	global_load_lds_dwordx4 v[216:217], off
	s_waitcnt vmcnt(8)
	s_waitcnt lgkmcnt(0)
	s_barrier
	s_setprio 1
	s_waitcnt lgkmcnt(0)
	v_mfma_f32_16x16x32_bf16 v[58:61], v[130:133], v[162:165], v[58:61]
	v_mfma_f32_16x16x32_bf16 v[62:65], v[138:141], v[162:165], v[62:65]
	v_mfma_f32_16x16x32_bf16 v[42:45], v[130:133], v[198:201], v[42:45]
	v_mfma_f32_16x16x32_bf16 v[46:49], v[138:141], v[198:201], v[46:49]
	v_mfma_f32_16x16x32_bf16 v[26:29], v[130:133], v[206:209], v[26:29]
	v_mfma_f32_16x16x32_bf16 v[30:33], v[138:141], v[206:209], v[30:33]
	v_mfma_f32_16x16x32_bf16 v[10:13], v[130:133], v[220:223], v[10:13]
	v_mfma_f32_16x16x32_bf16 v[14:17], v[138:141], v[220:223], v[14:17]
	v_mfma_f32_16x16x32_bf16 v[58:61], v[134:137], v[166:169], v[58:61]
	v_mfma_f32_16x16x32_bf16 v[62:65], v[142:145], v[166:169], v[62:65]
	v_mfma_f32_16x16x32_bf16 v[42:45], v[134:137], v[202:205], v[42:45]
	v_mfma_f32_16x16x32_bf16 v[46:49], v[142:145], v[202:205], v[46:49]
	v_mfma_f32_16x16x32_bf16 v[26:29], v[134:137], v[210:213], v[26:29]
	v_mfma_f32_16x16x32_bf16 v[30:33], v[142:145], v[210:213], v[30:33]
	v_mfma_f32_16x16x32_bf16 v[10:13], v[134:137], v[224:227], v[10:13]
	v_mfma_f32_16x16x32_bf16 v[14:17], v[142:145], v[224:227], v[14:17]
	v_mfma_f32_16x16x32_bf16 v[50:53], v[146:149], v[162:165], v[50:53]
	v_mfma_f32_16x16x32_bf16 v[54:57], v[154:157], v[162:165], v[54:57]
	v_mfma_f32_16x16x32_bf16 v[34:37], v[146:149], v[198:201], v[34:37]
	v_mfma_f32_16x16x32_bf16 v[38:41], v[154:157], v[198:201], v[38:41]
	v_mfma_f32_16x16x32_bf16 v[18:21], v[146:149], v[206:209], v[18:21]
	v_mfma_f32_16x16x32_bf16 v[22:25], v[154:157], v[206:209], v[22:25]
	v_mfma_f32_16x16x32_bf16 v[2:5], v[146:149], v[220:223], v[2:5]
	v_mfma_f32_16x16x32_bf16 v[6:9], v[154:157], v[220:223], v[6:9]
	v_mfma_f32_16x16x32_bf16 v[50:53], v[150:153], v[166:169], v[50:53]
	v_mfma_f32_16x16x32_bf16 v[54:57], v[158:161], v[166:169], v[54:57]
	v_mfma_f32_16x16x32_bf16 v[34:37], v[150:153], v[202:205], v[34:37]
	v_mfma_f32_16x16x32_bf16 v[38:41], v[158:161], v[202:205], v[38:41]
	v_mfma_f32_16x16x32_bf16 v[18:21], v[150:153], v[210:213], v[18:21]
	v_mfma_f32_16x16x32_bf16 v[22:25], v[158:161], v[210:213], v[22:25]
	v_mfma_f32_16x16x32_bf16 v[2:5], v[150:153], v[224:227], v[2:5]
	v_mfma_f32_16x16x32_bf16 v[6:9], v[158:161], v[224:227], v[6:9]
	s_setprio 0
	s_barrier
	s_add_i32 s84, 0, 0x18000
	v_add_u32_e32 v0, s84, v215
	s_add_i32 s85, 0, 0x1c000
	ds_read_b128 v[130:133], v0
	ds_read_b128 v[134:137], v0 offset:1024
	ds_read_b128 v[138:141], v0 offset:2048
	ds_read_b128 v[142:145], v0 offset:3072
	v_add_u32_e32 v0, s85, v215
	ds_read_b128 v[146:149], v0
	ds_read_b128 v[150:153], v0 offset:1024
	ds_read_b128 v[154:157], v0 offset:2048
	ds_read_b128 v[158:161], v0 offset:3072
	s_add_u32 s18, s18, 0x40000
	s_addc_u32 s19, s19, 0
	s_mov_b32 m0, s62
	ds_read_b128 v[162:165], v218 offset:32768
	ds_read_b128 v[166:169], v218 offset:33792
	ds_read_b128 v[198:201], v218 offset:34816
	ds_read_b128 v[202:205], v218 offset:35840
	ds_read_b128 v[206:209], v218 offset:36864
	ds_read_b128 v[210:213], v218 offset:37888
	ds_read_b128 v[220:223], v218 offset:38912
	ds_read_b128 v[224:227], v218 offset:39936
	s_nop 0
	v_lshl_add_u64 v[216:217], s[18:19], 0, v[196:197]
	global_load_lds_dwordx4 v[216:217], off
	v_lshl_add_u64 v[216:217], s[18:19], 0, v[172:173]
	s_mov_b32 m0, s63
	s_nop 0
	global_load_lds_dwordx4 v[216:217], off
	s_waitcnt vmcnt(8)
	s_waitcnt lgkmcnt(0)
	s_barrier
	s_setprio 1
	s_waitcnt lgkmcnt(0)
	v_mfma_f32_16x16x32_bf16 v[122:125], v[130:133], v[162:165], v[122:125]
	v_mfma_f32_16x16x32_bf16 v[126:129], v[138:141], v[162:165], v[126:129]
	v_mfma_f32_16x16x32_bf16 v[106:109], v[130:133], v[198:201], v[106:109]
	v_mfma_f32_16x16x32_bf16 v[110:113], v[138:141], v[198:201], v[110:113]
	v_mfma_f32_16x16x32_bf16 v[90:93], v[130:133], v[206:209], v[90:93]
	v_mfma_f32_16x16x32_bf16 v[94:97], v[138:141], v[206:209], v[94:97]
	v_mfma_f32_16x16x32_bf16 v[74:77], v[130:133], v[220:223], v[74:77]
	v_mfma_f32_16x16x32_bf16 v[78:81], v[138:141], v[220:223], v[78:81]
	v_mfma_f32_16x16x32_bf16 v[122:125], v[134:137], v[166:169], v[122:125]
	v_mfma_f32_16x16x32_bf16 v[126:129], v[142:145], v[166:169], v[126:129]
	v_mfma_f32_16x16x32_bf16 v[106:109], v[134:137], v[202:205], v[106:109]
	v_mfma_f32_16x16x32_bf16 v[110:113], v[142:145], v[202:205], v[110:113]
	v_mfma_f32_16x16x32_bf16 v[90:93], v[134:137], v[210:213], v[90:93]
	v_mfma_f32_16x16x32_bf16 v[94:97], v[142:145], v[210:213], v[94:97]
	v_mfma_f32_16x16x32_bf16 v[74:77], v[134:137], v[224:227], v[74:77]
	v_mfma_f32_16x16x32_bf16 v[78:81], v[142:145], v[224:227], v[78:81]
	v_mfma_f32_16x16x32_bf16 v[114:117], v[146:149], v[162:165], v[114:117]
	v_mfma_f32_16x16x32_bf16 v[118:121], v[154:157], v[162:165], v[118:121]
	v_mfma_f32_16x16x32_bf16 v[98:101], v[146:149], v[198:201], v[98:101]
	v_mfma_f32_16x16x32_bf16 v[102:105], v[154:157], v[198:201], v[102:105]
	v_mfma_f32_16x16x32_bf16 v[82:85], v[146:149], v[206:209], v[82:85]
	v_mfma_f32_16x16x32_bf16 v[86:89], v[154:157], v[206:209], v[86:89]
	v_mfma_f32_16x16x32_bf16 v[66:69], v[146:149], v[220:223], v[66:69]
	v_mfma_f32_16x16x32_bf16 v[70:73], v[154:157], v[220:223], v[70:73]
	v_mfma_f32_16x16x32_bf16 v[114:117], v[150:153], v[166:169], v[114:117]
	v_mfma_f32_16x16x32_bf16 v[118:121], v[158:161], v[166:169], v[118:121]
	v_mfma_f32_16x16x32_bf16 v[98:101], v[150:153], v[202:205], v[98:101]
	v_mfma_f32_16x16x32_bf16 v[102:105], v[158:161], v[202:205], v[102:105]
	v_mfma_f32_16x16x32_bf16 v[82:85], v[150:153], v[210:213], v[82:85]
	v_mfma_f32_16x16x32_bf16 v[86:89], v[158:161], v[210:213], v[86:89]
	v_mfma_f32_16x16x32_bf16 v[66:69], v[150:153], v[224:227], v[66:69]
	v_mfma_f32_16x16x32_bf16 v[70:73], v[158:161], v[224:227], v[70:73]
	s_setprio 0
	s_barrier
	s_add_u32 s18, s54, 0x80
	s_addc_u32 s19, s55, 0
	s_add_i32 s84, s84, s56
	ds_read_b128 v[162:165], v218 offset:49152
	ds_read_b128 v[166:169], v218 offset:50176
	ds_read_b128 v[198:201], v218 offset:51200
	ds_read_b128 v[202:205], v218 offset:52224
	ds_read_b128 v[206:209], v218 offset:53248
	ds_read_b128 v[210:213], v218 offset:54272
	ds_read_b128 v[220:223], v218 offset:55296
	ds_read_b128 v[224:227], v218 offset:56320
	s_mov_b32 m0, s84
	v_lshl_add_u64 v[216:217], s[18:19], 0, v[194:195]
	global_load_lds_dwordx4 v[216:217], off
	s_add_i32 m0, s84, 0x2000
	v_lshl_add_u64 v[216:217], s[18:19], 0, v[170:171]
	s_add_u32 s18, s54, 0x40080
	s_addc_u32 s19, s55, 0
	s_add_i32 s54, s85, s56
	global_load_lds_dwordx4 v[216:217], off
	s_mov_b32 m0, s54
	v_lshl_add_u64 v[216:217], s[18:19], 0, v[194:195]
	global_load_lds_dwordx4 v[216:217], off
	v_lshl_add_u64 v[216:217], s[18:19], 0, v[170:171]
	s_add_i32 m0, s54, 0x2000
	s_nop 0
	global_load_lds_dwordx4 v[216:217], off
	s_mov_b32 m0, s70
	v_lshl_add_u64 v[216:217], s[26:27], 0, v[196:197]
	global_load_lds_dwordx4 v[216:217], off
	v_lshl_add_u64 v[216:217], s[26:27], 0, v[172:173]
	s_mov_b32 m0, s71
	s_nop 0
	global_load_lds_dwordx4 v[216:217], off
	s_waitcnt vmcnt(8)
	s_waitcnt lgkmcnt(0)
	s_barrier
	s_setprio 1
	s_waitcnt lgkmcnt(0)
	v_mfma_f32_16x16x32_bf16 v[58:61], v[130:133], v[162:165], v[58:61]
	v_mfma_f32_16x16x32_bf16 v[62:65], v[138:141], v[162:165], v[62:65]
	v_mfma_f32_16x16x32_bf16 v[42:45], v[130:133], v[198:201], v[42:45]
	v_mfma_f32_16x16x32_bf16 v[46:49], v[138:141], v[198:201], v[46:49]
	v_mfma_f32_16x16x32_bf16 v[26:29], v[130:133], v[206:209], v[26:29]
	v_mfma_f32_16x16x32_bf16 v[30:33], v[138:141], v[206:209], v[30:33]
	v_mfma_f32_16x16x32_bf16 v[10:13], v[130:133], v[220:223], v[10:13]
	v_mfma_f32_16x16x32_bf16 v[14:17], v[138:141], v[220:223], v[14:17]
	v_mfma_f32_16x16x32_bf16 v[58:61], v[134:137], v[166:169], v[58:61]
	v_mfma_f32_16x16x32_bf16 v[62:65], v[142:145], v[166:169], v[62:65]
	v_mfma_f32_16x16x32_bf16 v[42:45], v[134:137], v[202:205], v[42:45]
	v_mfma_f32_16x16x32_bf16 v[46:49], v[142:145], v[202:205], v[46:49]
	v_mfma_f32_16x16x32_bf16 v[26:29], v[134:137], v[210:213], v[26:29]
	v_mfma_f32_16x16x32_bf16 v[30:33], v[142:145], v[210:213], v[30:33]
	v_mfma_f32_16x16x32_bf16 v[10:13], v[134:137], v[224:227], v[10:13]
	v_mfma_f32_16x16x32_bf16 v[14:17], v[142:145], v[224:227], v[14:17]
	v_mfma_f32_16x16x32_bf16 v[50:53], v[146:149], v[162:165], v[50:53]
	v_mfma_f32_16x16x32_bf16 v[54:57], v[154:157], v[162:165], v[54:57]
	v_mfma_f32_16x16x32_bf16 v[34:37], v[146:149], v[198:201], v[34:37]
	v_mfma_f32_16x16x32_bf16 v[38:41], v[154:157], v[198:201], v[38:41]
	v_mfma_f32_16x16x32_bf16 v[18:21], v[146:149], v[206:209], v[18:21]
	v_mfma_f32_16x16x32_bf16 v[22:25], v[154:157], v[206:209], v[22:25]
	v_mfma_f32_16x16x32_bf16 v[2:5], v[146:149], v[220:223], v[2:5]
	v_mfma_f32_16x16x32_bf16 v[6:9], v[154:157], v[220:223], v[6:9]
	v_mfma_f32_16x16x32_bf16 v[50:53], v[150:153], v[166:169], v[50:53]
	v_mfma_f32_16x16x32_bf16 v[54:57], v[158:161], v[166:169], v[54:57]
	v_mfma_f32_16x16x32_bf16 v[34:37], v[150:153], v[202:205], v[34:37]
	v_mfma_f32_16x16x32_bf16 v[38:41], v[158:161], v[202:205], v[38:41]
	v_mfma_f32_16x16x32_bf16 v[18:21], v[150:153], v[210:213], v[18:21]
	v_mfma_f32_16x16x32_bf16 v[22:25], v[158:161], v[210:213], v[22:25]
	v_mfma_f32_16x16x32_bf16 v[2:5], v[150:153], v[224:227], v[2:5]
	v_mfma_f32_16x16x32_bf16 v[6:9], v[158:161], v[224:227], v[6:9]
	s_setprio 0
	s_barrier
	s_add_u32 s79, s79, 0x100
	s_addc_u32 s80, s80, 0
	s_add_u32 s81, s81, 0x100
	s_addc_u32 s82, s82, 0
	s_cmp_ge_i32 s83, s69
	s_mov_b32 s18, s83
	s_cbranch_scc0 .LBB0_1405
	s_movk_i32 s87, 0x2000
	s_mov_b32 s78, 0x1a000
	s_mov_b32 s79, 0x8000
	s_mov_b32 s80, 0x1e000
	s_mov_b32 s81, 0xc000
	s_mov_b32 s82, 0xe000
	s_mov_b32 s83, 0xb000
	s_mov_b32 s84, 0x4ffff
	s_mov_b32 s85, 0x66666667
	s_mov_b32 s86, 0x1f000
